# static s_setprio 1 for waves 4-7 across the M3 phase (younger half carries the extra o-MFMAs and stores in the GDN scan); reset at phase end
# speedup vs baseline: 1.0043x; 1.0043x over previous
.LBB0_1540:
	v_readfirstlane_b32 s100, v0
	s_lshr_b32 s100, s100, 6
	s_cmp_ge_u32 s100, 4
	s_cbranch_scc0 .Lm3_prio_skip
	s_setprio 1

.LBB0_2104:
	s_setprio 0
	v_readlane_b32 s0, v253, 46
	v_readlane_b32 s4, v252, 0
	s_add_i32 s2, s0, 10
	v_readlane_b32 s7, v252, 3
	v_readlane_b32 s30, v253, 35
	s_cmp_ge_i32 s2, s7
	v_readlane_b32 s31, v253, 36
	v_readlane_b32 s5, v252, 1
	v_readlane_b32 s6, v252, 2
	s_cbranch_scc1 .LBB0_2154
	s_waitcnt vmcnt(0)
	s_waitcnt vmcnt(0) lgkmcnt(0)
	s_barrier
	s_mov_b64 s[4:5], exec
	v_readlane_b32 s0, v253, 23
	v_readlane_b32 s1, v253, 24
	s_and_b64 s[0:1], s[4:5], s[0:1]
	s_mov_b64 exec, s[0:1]
	s_cbranch_execz .LBB0_2153
	v_readlane_b32 s0, v253, 11
	s_waitcnt vmcnt(0) expcnt(0) lgkmcnt(0)
	s_nop 0
	v_mov_b32_e32 v2, s0
	ds_read_b32 v4, v2
	v_readlane_b32 s0, v253, 12
	s_waitcnt lgkmcnt(0)
	v_cmp_ne_u32_e32 vcc, 0, v4
	v_mov_b32_e32 v2, s0
	ds_read_b32 v2, v2
	s_cbranch_vccnz .LBB0_2121
	v_readlane_b32 s6, v252, 4
	v_readlane_b32 s7, v252, 5
	s_load_dwordx2 s[0:1], s[6:7], 0x4
	s_mov_b32 s10, 1
	s_waitcnt lgkmcnt(0)
	s_mul_i32 s3, s0, s54
	s_mul_i32 s3, s3, s1
	s_branch .LBB0_2109
